# version 97 plus: no store-drain wait (vmcnt 0) between the residual GEMM unit and the sample-row tile that follows it
# baseline (speedup 1.0000x reference)
; #define LAS __attribute__((address_space(3)))
; __device__ __forceinline__ void srg_phase(LAS unsigned char* L, const bf16* Aop, const bf16* Bt, const int K, bf16* xb, float* rowss, const float scale, const bool fin, const int G, const int tid) {
;     const int w = __builtin_amdgcn_readfirstlane(tid >> 6), lane = tid & 63, q = lane >> 4, r16 = lane & 15, wm = w >> 1, wn = w & 1;
;     const int lr = tid >> 3, lc = (tid & 7) * 8;
;     const int nt = K / 128;
;     for (int tile = blockIdx.x; tile < 256; tile += G) {
;         const int tm = tile >> 4, tn = tile & 15;
;         const bf16* ag = Aop + (size_t)(MP + 64 * tm + lr) * K + lc;
;         const bf16* bg = Bt + (size_t)(64 * tn + lr) * K + lc;
;         f32x4 acc0 = {0.f, 0.f, 0.f, 0.f}, acc1 = acc0;
;         v4u ra[2][2], rb[2][2];
; #pragma unroll
;         for (int i = 0; i < 2; ++i) { ra[i][0] = *(const v4u*)(ag + i * 128); ra[i][1] = *(const v4u*)(ag + i * 128 + 64); rb[i][0] = *(const v4u*)(bg + i * 128); rb[i][1] = *(const v4u*)(bg + i * 128 + 64); }
;         LAS unsigned char* wr0 = L + lr * 272 + lc * 2;
;         const LAS unsigned char* fa = L + (16 * wm + r16) * 272 + (8 * q) * 2;
;         const LAS unsigned char* fb = L + 17408 + (32 * wn + r16) * 272 + (8 * q) * 2;
; __global__ void __launch_bounds__(NTHREADS, 2) mk_fwd(Args args) {
;     ...
;                 if (srg_first) srg_phase(ldsl + RING_OFF, Aop, (const bf16*)(wl + wo), K, xb, rso, esc, efin, G, tidv);
;                 pg8::gemm_phase<pg8::EpiResid, pg8::StaticOrder, PG8_ALIGN, PG8_SP2>(ldsl + RING_OFF, g, S, E, tidv);
;                 if (!srg_first)
;     ...
;                 srg_phase(ldsl + RING_OFF, Aop, (const bf16*)(wl + wo), K, xb, rso, 0.5f * esc, false, G, tidv);
;                 srg_phase(ldsl + RING_OFF, Aop, (const bf16*)(wl + wo), K, xb, rso, 0.5f * esc, efin, G, tidv);
;     ...
;                 srg_phase(ldsl + RING_OFF, Aop, (const bf16*)(wl + wo), K, xb, rso, esc, efin, G, tidv);
.LBB0_187:
	v_readlane_b32 s34, v254, 50
	v_readlane_b32 s35, v254, 51
	s_movk_i32 s31, 0x2000
	s_mov_b32 s19, s68
	s_barrier
.LBB0_188:
	v_readlane_b32 s0, v251, 58
	v_readlane_b32 s1, v251, 59
	s_andn2_b64 vcc, exec, s[0:1]
	s_cbranch_vccnz .LBB0_196
	s_and_b64 vcc, exec, s[36:37]
	v_readfirstlane_b32 s0, v244
	s_cbranch_vccnz .LBB0_196
	v_lshlrev_b32_e32 v6, 4, v244
	s_ashr_i32 s1, s0, 3
	s_lshr_b32 s0, s0, 1
	v_ashrrev_i32_e32 v54, 3, v244
	v_and_b32_e32 v6, 0x70, v6
	s_waitcnt lgkmcnt(0)
	v_mov_b32_e32 v7, v4
	s_movk_i32 s11, 0x110
	v_and_or_b32 v55, s1, -16, v245
	s_and_b32 s0, s0, 32
	v_lshl_add_u64 v[46:47], s[20:21], 0, v[6:7]
	v_lshl_add_u64 v[48:49], s[24:25], 0, v[6:7]
	v_mul_lo_u32 v7, v54, s11
	v_mul_lo_u32 v8, v55, s11
	s_waitcnt lgkmcnt(0)
	v_or_b32_e32 v9, s0, v245
	v_add_u32_e32 v7, 0, v7
	v_add_u32_e32 v8, 0, v8
	v_mad_u32_u24 v9, v9, s11, 0
	s_lshr_b32 s10, s3, 7
	v_lshl_or_b32 v56, v3, 2, s0
	v_cmp_eq_u32_e64 s[36:37], 0, v3
	v_mov_b32_e32 v3, v2
	v_add_u32_e32 v57, v7, v6
	v_add_u32_e32 v58, v8, v5
	v_add_u32_e32 v5, v9, v5
	s_mov_b32 s11, s2
	s_branch .LBB0_192
